# lost v_max3 in the diff-attention odd step restored; P1 epilogue vmcnt(0) relaxations; P5 fused epilogue residual loads hoisted
# baseline (speedup 1.0000x reference)
.LBB0_418:
	v_add_u32_e32 v225, s34, v192
	s_add_i32 s34, s30, 0x2000
	s_and_b32 s55, s34, 0x6000
	v_add_u32_e32 v114, s55, v191
	ds_read_b128 v[226:229], v114 offset:2560
	v_add_f32_e32 v86, v98, v99
	v_cvt_pk_bf16_f32 v126, v98, v99
	s_waitcnt lgkmcnt(1)
	v_mfma_f32_32x32x16_bf16 v[98:113], v[82:85], v[244:247], v[66:81]
	v_add_f32_e32 v86, v127, v86
	v_add_f32_e32 v86, v223, v86
	v_add_f32_e32 v86, v217, v86
	v_add_f32_e32 v86, v219, v86
	v_cvt_pk_bf16_f32 v127, v127, v223
	ds_read_b128 v[234:237], v114 offset:4096
	v_add_f32_e32 v82, v222, v86
	v_add_f32_e32 v82, v224, v82
	v_add_f32_e32 v82, v214, v82
	v_add_f32_e32 v115, v122, v82
	v_mfma_f32_32x32x16_bf16 v[82:97], v[134:137], v[244:247], v[66:81]
	v_cvt_pk_bf16_f32 v128, v217, v219
	v_cvt_pk_bf16_f32 v129, v222, v224
	ds_read_b128 v[134:137], v114 offset:4608
	s_waitcnt lgkmcnt(2)
	v_mfma_f32_32x32x16_bf16 v[98:113], v[130:133], v[248:251], v[98:113]
	v_add_f32_e32 v115, v123, v115
	v_add_f32_e32 v115, v220, v115
	v_add_f32_e32 v115, v216, v115
	v_add_f32_e32 v115, v218, v115
	v_cvt_pk_bf16_f32 v122, v214, v122
	v_cvt_pk_bf16_f32 v123, v123, v220
	ds_read_b128 v[130:133], v114 offset:6144
	v_mfma_f32_32x32x16_bf16 v[82:97], v[226:229], v[248:251], v[82:97]
	v_add_f32_e32 v115, v215, v115
	v_add_f32_e32 v115, v221, v115
	v_add_f32_e32 v115, v203, v115
	v_add_f32_e32 v115, v206, v115
	v_cvt_pk_bf16_f32 v124, v216, v218
	v_cvt_pk_bf16_f32 v125, v215, v221
	ds_read_b128 v[214:217], v114 offset:6656
	ds_read_b128 v[218:221], v201 offset:3072
	s_waitcnt lgkmcnt(3)
	v_mfma_f32_32x32x16_bf16 v[98:113], v[234:237], v[252:255], v[98:113]
	v_add_f32_e32 v114, v212, v115
	v_add_f32_e32 v114, v213, v114
	v_add_f32_e32 v114, v142, v114
	v_add_f32_e32 v114, v209, v114
	v_cvt_pk_bf16_f32 v118, v203, v206
	v_cvt_pk_bf16_f32 v119, v212, v213
	ds_read_b64_tr_b16 v[226:227], v225 offset:32768
	ds_read_b64_tr_b16 v[228:229], v225 offset:33280
	v_mfma_f32_32x32x16_bf16 v[82:97], v[134:137], v[252:255], v[82:97]
	v_add_f32_e32 v114, v204, v114
	v_add_f32_e32 v114, v207, v114
	v_add_f32_e32 v114, v144, v114
	v_add_f32_e32 v114, v202, v114
	v_cvt_pk_bf16_f32 v120, v142, v209
	v_cvt_pk_bf16_f32 v121, v204, v207
	ds_read_b64_tr_b16 v[134:135], v225 offset:36864
	ds_read_b64_tr_b16 v[136:137], v225 offset:37376
	s_waitcnt lgkmcnt(4)
	v_mfma_f32_32x32x16_bf16 v[98:113], v[130:133], v[218:221], v[98:113]
	v_add_f32_e32 v114, v205, v114
	v_add_f32_e32 v114, v210, v114
	v_add_f32_e32 v114, v143, v114
	v_add_f32_e32 v130, v145, v114
	v_cvt_pk_bf16_f32 v114, v144, v202
	v_cvt_pk_bf16_f32 v115, v205, v210
	ds_read_b64_tr_b16 v[138:139], v225 offset:40960
	ds_read_b64_tr_b16 v[140:141], v225 offset:41472
	v_mfma_f32_32x32x16_bf16 v[82:97], v[214:217], v[218:221], v[82:97]
	v_add_f32_e32 v116, v208, v130
	v_add_f32_e32 v130, v211, v116
	v_cvt_pk_bf16_f32 v116, v143, v145
	v_cvt_pk_bf16_f32 v117, v208, v211
	s_waitcnt lgkmcnt(4)
	v_mfma_f32_32x32x16_bf16 v[2:17], v[126:129], v[226:229], v[2:17]
	ds_read_b64_tr_b16 v[142:143], v225 offset:45056
	ds_read_b64_tr_b16 v[144:145], v225 offset:45568
	v_add_f32_e32 v202, v146, v130
	s_nop 2
	v_max3_f32 v130, v98, v99, v82
	v_max3_f32 v131, v100, v101, v83
	v_max3_f32 v130, v130, v84, v85
	v_max3_f32 v146, v130, v102, v103
	v_max3_f32 v203, v131, v104, v105
	s_waitcnt lgkmcnt(4)
	v_mfma_f32_32x32x16_bf16 v[50:65], v[126:129], v[134:137], v[50:65]
	ds_read_b64_tr_b16 v[130:131], v225 offset:33792
	ds_read_b64_tr_b16 v[132:133], v225 offset:34304
	s_add_i32 s34, s30, 0x8000
	s_and_b32 s34, s34, 0x6000
	v_lshl_add_u64 v[134:135], v[178:179], 0, s[30:31]
	s_add_i32 s34, s34, s89
	s_mov_b32 m0, s34
	s_nop 0
	global_load_lds_dwordx4 v[134:135], off
	v_max3_f32 v134, v146, v86, v87
	v_max3_f32 v135, v203, v88, v89
	v_max3_f32 v146, v134, v106, v107
	v_max3_f32 v203, v135, v108, v109
	s_waitcnt lgkmcnt(4)
	v_mfma_f32_32x32x16_bf16 v[34:49], v[126:129], v[138:141], v[34:49]
	s_movk_i32 s34, 0xc000
	s_mov_b32 s35, -1
	ds_read_b64_tr_b16 v[134:135], v225 offset:37888
	ds_read_b64_tr_b16 v[136:137], v225 offset:38400
	v_lshl_add_u64 v[138:139], v[180:181], 0, s[34:35]
	s_add_i32 s36, s2, s97
	s_mov_b32 m0, s36
	s_nop 0
	global_load_lds_dwordx4 v[138:139], off
	global_load_lds_dwordx4 v[138:139], off offset:1024
	v_max3_f32 v138, v146, v90, v91
	v_max3_f32 v139, v203, v92, v93
	v_max3_f32 v146, v138, v110, v111
	v_max3_f32 v203, v139, v112, v113
	s_waitcnt lgkmcnt(4)
	v_mfma_f32_32x32x16_bf16 v[18:33], v[126:129], v[142:145], v[18:33]
	v_max3_f32 v126, v146, v94, v95
	v_max3_f32 v127, v203, v96, v97
	ds_read_b64_tr_b16 v[138:139], v225 offset:41984
	ds_read_b64_tr_b16 v[140:141], v225 offset:42496
	v_max_f32 v126, v126, v127
	s_nop 0
	v_mov_b32_e32 v127, v126
	s_nop 1
	v_permlane32_swap_b32_e32 v126, v127
	v_max_f32 v126, v126, v127
	s_nop 0
	v_cmp_lt_f32_e32 vcc, s49, v126
	s_cmp_lg_u64 vcc, 0
	s_cselect_b64 s[36:37], -1, 0
	s_cbranch_vccnz .LBB0_451

; __device__ __forceinline__ f32x4 bf4_to_f32(u32x2 w) { f32x4 r; r[0] = __uint_as_float(w.x << 16); r[1] = __uint_as_float(w.x & 0xffff0000u); r[2] = __uint_as_float(w.y << 16); r[3] = __uint_as_float(w.y & 0xffff0000u); return r; }
;     __device__ __forceinline__ void fused(f32x4 (&acc)[2][2][4][2], const Unit& u, int wr, int wc, int fr, int fq, PG8_LAS unsigned char* lds, int wid, int lane) const {
;     ...
;         const int col0 = u.pn * BM + wc * 32 + 4 * fq;
;         float r2[8];
; #pragma unroll
;         for (int g = 0; g < 8; ++g) r2[g] = __hip_atomic_load(rs2 + u.pm * BM + (g >> 2) * HALF + wr * 64 + (g & 3) * 16 + fr, __ATOMIC_RELAXED, __HIP_MEMORY_SCOPE_AGENT);
; #pragma unroll
;         for (int ai = 0; ai < 2; ++ai)
; #pragma unroll
;             for (int m = 0; m < 4; ++m) { const int r = ai * HALF + wr * 64 + m * 16 + fr; const size_t off = (size_t)(u.pm * BM + r) * 2048 + col0; float s = 0.f;
;                 const float rr = __builtin_amdgcn_rcpf(r2[ai * 4 + m] * (1.0f / 2048.0f) + 1e-5f);
; #pragma unroll
;                 for (int bj = 0; bj < 2; ++bj)
; #pragma unroll
;                     for (int n = 0; n < 2; ++n) { const f32x4 bs = bf4_to_f32(*(const u32x2*)(base + off + bj * HALF + n * 16)); const f32x4 o = bs + acc[ai][bj][m][n] * rr; acc[ai][bj][m][n] = o;
;                         s += (o[0] * o[0] + o[1] * o[1]) + (o[2] * o[2] + o[3] * o[3]); }
;                 s += __shfl_xor(s, 16); s += __shfl_xor(s, 32);
;                 if (fq == 0) P[r * 4 + wc] = s; }
.LBB0_1034:
	s_lshl_b32 s0, s64, 8
	s_ashr_i32 s1, s0, 31
	s_lshl_b32 s4, s18, 5
	s_lshl_b64 s[2:3], s[0:1], 2
	s_add_u32 s1, s6, s2
	s_addc_u32 s3, s7, s3
	s_lshl_b32 s2, s24, 2
	s_add_u32 s2, s1, s2
	s_addc_u32 s3, s3, 0
	s_lshl_b32 s1, s16, 8
	v_add_u32_e32 v130, s0, v162
	s_or_b32 s1, s1, s4
	v_ashrrev_i32_e32 v131, 31, v130
	v_and_or_b32 v160, v138, 12, s1
	v_lshlrev_b64 v[132:133], 12, v[130:131]
	v_mov_b32_e32 v141, 0
	v_lshl_add_u64 v[132:133], s[70:71], 0, v[132:133]
	v_lshlrev_b32_e32 v140, 1, v160
	v_lshlrev_b32_e32 v1, 2, v1
	v_lshl_add_u64 v[132:133], v[132:133], 0, v[140:141]
	v_mov_b64_e32 v[196:197], v[132:133]
	s_barrier
	global_load_dword v137, v1, s[2:3] sc1
	global_load_dword v134, v1, s[2:3] offset:64 sc1
	global_load_dword v136, v1, s[2:3] offset:128 sc1
	global_load_dword v139, v1, s[2:3] offset:192 sc1
	global_load_dword v142, v1, s[2:3] offset:512 sc1
	global_load_dword v144, v1, s[2:3] offset:576 sc1
	global_load_dword v146, v1, s[2:3] offset:640 sc1
	s_nop 0
	global_load_dword v1, v1, s[2:3] offset:704 sc1
	s_nop 0
	global_load_dwordx2 v[148:149], v[132:133], off
	global_load_dwordx2 v[150:151], v[132:133], off offset:32
	global_load_dwordx2 v[152:153], v[132:133], off offset:256
	s_nop 0
	global_load_dwordx2 v[132:133], v[132:133], off offset:288
	s_mov_b64 s[98:99], 0x10000
	v_lshl_add_u64 v[198:199], v[196:197], 0, s[98:99]
	global_load_dwordx2 v[202:203], v[198:199], off
	global_load_dwordx2 v[204:205], v[198:199], off offset:32
	global_load_dwordx2 v[206:207], v[198:199], off offset:256
	global_load_dwordx2 v[208:209], v[198:199], off offset:288
	s_mov_b64 s[98:99], 0x20000
	v_lshl_add_u64 v[200:201], v[196:197], 0, s[98:99]
	global_load_dwordx2 v[210:211], v[200:201], off
	global_load_dwordx2 v[212:213], v[200:201], off offset:32
	global_load_dwordx2 v[214:215], v[200:201], off offset:256
	global_load_dwordx2 v[216:217], v[200:201], off offset:288
	s_mov_b64 s[98:99], 0x30000
	v_lshl_add_u64 v[198:199], v[196:197], 0, s[98:99]
	global_load_dwordx2 v[218:219], v[198:199], off
	global_load_dwordx2 v[220:221], v[198:199], off offset:32
	global_load_dwordx2 v[222:223], v[198:199], off offset:256
	global_load_dwordx2 v[224:225], v[198:199], off offset:288
	s_mov_b64 s[98:99], 0x80000
	v_lshl_add_u64 v[200:201], v[196:197], 0, s[98:99]
	global_load_dwordx2 v[226:227], v[200:201], off
	global_load_dwordx2 v[228:229], v[200:201], off offset:32
	global_load_dwordx2 v[230:231], v[200:201], off offset:256
	global_load_dwordx2 v[232:233], v[200:201], off offset:288
	s_mov_b64 s[98:99], 0x90000
	v_lshl_add_u64 v[198:199], v[196:197], 0, s[98:99]
	global_load_dwordx2 v[234:235], v[198:199], off
	global_load_dwordx2 v[236:237], v[198:199], off offset:32
	global_load_dwordx2 v[238:239], v[198:199], off offset:256
	global_load_dwordx2 v[240:241], v[198:199], off offset:288
	s_mov_b64 s[98:99], 0xa0000
	v_lshl_add_u64 v[200:201], v[196:197], 0, s[98:99]
	global_load_dwordx2 v[244:245], v[200:201], off
	global_load_dwordx2 v[246:247], v[200:201], off offset:32
	global_load_dwordx2 v[248:249], v[200:201], off offset:256
	global_load_dwordx2 v[250:251], v[200:201], off offset:288
	s_mov_b64 s[98:99], 0xb0000
	v_lshl_add_u64 v[198:199], v[196:197], 0, s[98:99]
	global_load_dwordx2 v[252:253], v[198:199], off
	global_load_dwordx2 v[254:255], v[198:199], off offset:32
	global_load_dwordx2 v[188:189], v[198:199], off offset:256
	global_load_dwordx2 v[190:191], v[198:199], off offset:288
	v_mbcnt_lo_u32_b32 v138, -1, 0
	v_mbcnt_hi_u32_b32 v143, -1, v138
	v_and_b32_e32 v145, 64, v143
	v_xor_b32_e32 v138, 16, v143
	v_add_u32_e32 v145, 64, v145
	v_mov_b32_e32 v135, 0x3727c5ac
	v_cmp_lt_i32_e32 vcc, v138, v145
	s_lshl_b32 s1, s18, 2
	s_add_i32 s1, s1, 0
	v_cndmask_b32_e32 v138, v143, v138, vcc
	v_lshlrev_b32_e32 v161, 2, v138
	s_waitcnt vmcnt(28)
	v_fmamk_f32 v137, v137, 0x3a000000, v135
	v_rcp_f32_e32 v138, v137
	v_lshlrev_b32_e32 v154, 16, v148
	v_and_b32_e32 v155, 0xffff0000, v148
	v_lshlrev_b32_e32 v148, 16, v149
	v_and_b32_e32 v149, 0xffff0000, v149
	v_lshlrev_b32_e32 v156, 16, v150
	v_and_b32_e32 v157, 0xffff0000, v150
	v_lshlrev_b32_e32 v150, 16, v151
	v_and_b32_e32 v151, 0xffff0000, v151
	v_lshlrev_b32_e32 v158, 16, v152
	v_and_b32_e32 v159, 0xffff0000, v152
	v_lshlrev_b32_e32 v152, 16, v153
	v_and_b32_e32 v153, 0xffff0000, v153
	v_lshlrev_b32_e32 v164, 16, v132
	v_and_b32_e32 v165, 0xffff0000, v132
	v_lshlrev_b32_e32 v132, 16, v133
	v_and_b32_e32 v133, 0xffff0000, v133
	v_pk_fma_f32 v[128:129], v[128:129], v[138:139], v[148:149] op_sel_hi:[1,0,1]
	v_pk_fma_f32 v[126:127], v[126:127], v[138:139], v[154:155] op_sel_hi:[1,0,1]
	v_pk_fma_f32 v[124:125], v[124:125], v[138:139], v[150:151] op_sel_hi:[1,0,1]
	v_pk_fma_f32 v[122:123], v[122:123], v[138:139], v[156:157] op_sel_hi:[1,0,1]
	v_pk_fma_f32 v[120:121], v[120:121], v[138:139], v[152:153] op_sel_hi:[1,0,1]
	v_pk_fma_f32 v[118:119], v[118:119], v[138:139], v[158:159] op_sel_hi:[1,0,1]
	v_pk_fma_f32 v[116:117], v[116:117], v[138:139], v[132:133] op_sel_hi:[1,0,1]
	v_pk_fma_f32 v[114:115], v[114:115], v[138:139], v[164:165] op_sel_hi:[1,0,1]
	v_mul_f32_e32 v132, v127, v127
	v_mul_f32_e32 v133, v129, v129
	v_mul_f32_e32 v137, v123, v123
	v_mul_f32_e32 v138, v125, v125
	v_mul_f32_e32 v147, v119, v119
	v_mul_f32_e32 v148, v121, v121
	v_fmac_f32_e32 v132, v126, v126
	v_fmac_f32_e32 v133, v128, v128
	v_fmac_f32_e32 v137, v122, v122
	v_fmac_f32_e32 v138, v124, v124
	v_mul_f32_e32 v149, v115, v115
	v_mul_f32_e32 v150, v117, v117
	v_fmac_f32_e32 v147, v118, v118
	v_fmac_f32_e32 v148, v120, v120
	v_add_f32_e32 v132, v132, v133
	v_add_f32_e32 v133, v137, v138
	v_fmac_f32_e32 v149, v114, v114
	v_fmac_f32_e32 v150, v116, v116
	v_add_f32_e32 v137, v147, v148
	v_add_f32_e32 v132, v132, v133
	v_add_f32_e32 v132, v132, v137
	v_add_f32_e32 v133, v149, v150
	v_add_f32_e32 v132, v132, v133
	ds_bpermute_b32 v133, v161, v132
	v_xor_b32_e32 v137, 32, v143
	v_cmp_lt_i32_e32 vcc, v137, v145
	s_waitcnt lgkmcnt(0)
	v_add_f32_e32 v132, v132, v133
	v_cndmask_b32_e32 v137, v143, v137, vcc
	v_lshlrev_b32_e32 v163, 2, v137
	ds_bpermute_b32 v133, v163, v132
	v_cmp_gt_u32_e32 vcc, 16, v194
	s_and_saveexec_b64 s[2:3], vcc
	s_cbranch_execz .LBB0_1036
	v_lshl_add_u32 v137, v162, 4, s1
	s_waitcnt lgkmcnt(0)
	v_add_f32_e32 v132, v132, v133
	ds_write_b32 v137, v132
; __device__ __forceinline__ f32x4 bf4_to_f32(u32x2 w) { f32x4 r; r[0] = __uint_as_float(w.x << 16); r[1] = __uint_as_float(w.x & 0xffff0000u); r[2] = __uint_as_float(w.y << 16); r[3] = __uint_as_float(w.y & 0xffff0000u); return r; }
;     __device__ __forceinline__ void fused(f32x4 (&acc)[2][2][4][2], const Unit& u, int wr, int wc, int fr, int fq, PG8_LAS unsigned char* lds, int wid, int lane) const {
;     ...
;             for (int m = 0; m < 4; ++m) { const int r = ai * HALF + wr * 64 + m * 16 + fr; const size_t off = (size_t)(u.pm * BM + r) * 2048 + col0; float s = 0.f;
;                 const float rr = __builtin_amdgcn_rcpf(r2[ai * 4 + m] * (1.0f / 2048.0f) + 1e-5f);
; #pragma unroll
;                 for (int bj = 0; bj < 2; ++bj)
; #pragma unroll
;                     for (int n = 0; n < 2; ++n) { const f32x4 bs = bf4_to_f32(*(const u32x2*)(base + off + bj * HALF + n * 16)); const f32x4 o = bs + acc[ai][bj][m][n] * rr; acc[ai][bj][m][n] = o;
;                         s += (o[0] * o[0] + o[1] * o[1]) + (o[2] * o[2] + o[3] * o[3]); }
;                 s += __shfl_xor(s, 16); s += __shfl_xor(s, 32);
;                 if (fq == 0) P[r * 4 + wc] = s; }
.LBB0_1036:
	s_or_b64 exec, exec, s[2:3]
	v_or_b32_e32 v137, 16, v162
	v_add_u32_e32 v132, s0, v137
	s_waitcnt lgkmcnt(0)
	v_ashrrev_i32_e32 v133, 31, v132
	v_lshlrev_b64 v[148:149], 12, v[132:133]
	v_lshl_add_u64 v[148:149], s[70:71], 0, v[148:149]
	v_lshl_add_u64 v[148:149], v[148:149], 0, v[140:141]
	s_waitcnt vmcnt(0)
	v_mov_b64_e32 v[150:151], v[202:203]
	v_mov_b64_e32 v[152:153], v[204:205]
	v_mov_b64_e32 v[154:155], v[206:207]
	v_mov_b64_e32 v[148:149], v[208:209]
	s_nop 0
	v_fmac_f32_e32 v135, 0x3a000000, v134
	v_rcp_f32_e32 v134, v135
	s_waitcnt vmcnt(3)
	v_lshlrev_b32_e32 v156, 16, v150
	v_and_b32_e32 v157, 0xffff0000, v150
	v_lshlrev_b32_e32 v150, 16, v151
	v_and_b32_e32 v151, 0xffff0000, v151
	s_waitcnt vmcnt(2)
	v_lshlrev_b32_e32 v158, 16, v152
	v_and_b32_e32 v159, 0xffff0000, v152
	v_lshlrev_b32_e32 v152, 16, v153
	v_and_b32_e32 v153, 0xffff0000, v153
	s_waitcnt vmcnt(1)
	v_lshlrev_b32_e32 v164, 16, v154
	v_and_b32_e32 v165, 0xffff0000, v154
	v_lshlrev_b32_e32 v154, 16, v155
	v_and_b32_e32 v155, 0xffff0000, v155
	s_waitcnt vmcnt(0)
	v_lshlrev_b32_e32 v166, 16, v148
	v_and_b32_e32 v167, 0xffff0000, v148
	v_lshlrev_b32_e32 v148, 16, v149
	v_and_b32_e32 v149, 0xffff0000, v149
	v_pk_fma_f32 v[112:113], v[112:113], v[134:135], v[150:151] op_sel_hi:[1,0,1]
	v_pk_fma_f32 v[110:111], v[110:111], v[134:135], v[156:157] op_sel_hi:[1,0,1]
	v_pk_fma_f32 v[108:109], v[108:109], v[134:135], v[152:153] op_sel_hi:[1,0,1]
	v_pk_fma_f32 v[106:107], v[106:107], v[134:135], v[158:159] op_sel_hi:[1,0,1]
	v_pk_fma_f32 v[104:105], v[104:105], v[134:135], v[154:155] op_sel_hi:[1,0,1]
	v_pk_fma_f32 v[102:103], v[102:103], v[134:135], v[164:165] op_sel_hi:[1,0,1]
	v_pk_fma_f32 v[100:101], v[100:101], v[134:135], v[148:149] op_sel_hi:[1,0,1]
	v_pk_fma_f32 v[98:99], v[98:99], v[134:135], v[166:167] op_sel_hi:[1,0,1]
	v_mul_f32_e32 v134, v111, v111
	v_mul_f32_e32 v135, v113, v113
	v_mul_f32_e32 v138, v107, v107
	v_mul_f32_e32 v141, v109, v109
	v_mul_f32_e32 v143, v103, v103
	v_mul_f32_e32 v145, v105, v105
	v_fmac_f32_e32 v134, v110, v110
	v_fmac_f32_e32 v135, v112, v112
	v_fmac_f32_e32 v138, v106, v106
	v_fmac_f32_e32 v141, v108, v108
	v_mul_f32_e32 v147, v99, v99
	v_mul_f32_e32 v148, v101, v101
	v_fmac_f32_e32 v143, v102, v102
	v_fmac_f32_e32 v145, v104, v104
	v_add_f32_e32 v134, v134, v135
	v_add_f32_e32 v135, v138, v141
	v_fmac_f32_e32 v147, v98, v98
	v_fmac_f32_e32 v148, v100, v100
	v_add_f32_e32 v138, v143, v145
	v_add_f32_e32 v134, v134, v135
	v_add_f32_e32 v134, v134, v138
	v_add_f32_e32 v135, v147, v148
	v_add_f32_e32 v134, v134, v135
	ds_bpermute_b32 v135, v161, v134
	s_waitcnt lgkmcnt(0)
	v_add_f32_e32 v134, v134, v135
	ds_bpermute_b32 v135, v163, v134
	s_and_saveexec_b64 s[2:3], vcc
	s_cbranch_execz .LBB0_1038
	v_lshl_add_u32 v137, v137, 4, s1
	s_waitcnt lgkmcnt(0)
	v_add_f32_e32 v134, v134, v135
	ds_write_b32 v137, v134
.LBB0_1038:
	s_or_b64 exec, exec, s[2:3]
	v_or_b32_e32 v143, 32, v162
	v_add_u32_e32 v134, s0, v143
	s_waitcnt lgkmcnt(0)
	v_ashrrev_i32_e32 v135, 31, v134
	v_lshlrev_b64 v[148:149], 12, v[134:135]
	v_lshl_add_u64 v[148:149], s[70:71], 0, v[148:149]
	v_mov_b32_e32 v141, 0
	v_lshl_add_u64 v[148:149], v[148:149], 0, v[140:141]
	s_waitcnt vmcnt(0)
	v_mov_b64_e32 v[150:151], v[210:211]
	v_mov_b64_e32 v[152:153], v[212:213]
	v_mov_b64_e32 v[154:155], v[214:215]
	v_mov_b64_e32 v[148:149], v[216:217]
	s_nop 0
	v_mov_b32_e32 v138, 0x3727c5ac
	v_fmamk_f32 v136, v136, 0x3a000000, v138
	v_rcp_f32_e32 v156, v136
	s_waitcnt vmcnt(3)
	v_lshlrev_b32_e32 v136, 16, v150
	v_and_b32_e32 v137, 0xffff0000, v150
	v_lshlrev_b32_e32 v150, 16, v151
	v_and_b32_e32 v151, 0xffff0000, v151
	s_waitcnt vmcnt(2)
	v_lshlrev_b32_e32 v158, 16, v152
	v_and_b32_e32 v159, 0xffff0000, v152
	v_lshlrev_b32_e32 v152, 16, v153
	v_and_b32_e32 v153, 0xffff0000, v153
	s_waitcnt vmcnt(1)
	v_lshlrev_b32_e32 v164, 16, v154
	v_and_b32_e32 v165, 0xffff0000, v154
	v_lshlrev_b32_e32 v154, 16, v155
	v_and_b32_e32 v155, 0xffff0000, v155
	s_waitcnt vmcnt(0)
	v_lshlrev_b32_e32 v166, 16, v148
	v_and_b32_e32 v167, 0xffff0000, v148
	v_pk_fma_f32 v[96:97], v[96:97], v[156:157], v[150:151] op_sel_hi:[1,0,1]
	v_pk_fma_f32 v[136:137], v[94:95], v[156:157], v[136:137] op_sel_hi:[1,0,1]
	v_pk_fma_f32 v[92:93], v[92:93], v[156:157], v[152:153] op_sel_hi:[1,0,1]
	v_pk_fma_f32 v[94:95], v[90:91], v[156:157], v[158:159] op_sel_hi:[1,0,1]
	v_lshlrev_b32_e32 v148, 16, v149
	v_and_b32_e32 v149, 0xffff0000, v149
	v_pk_fma_f32 v[88:89], v[88:89], v[156:157], v[154:155] op_sel_hi:[1,0,1]
	v_pk_fma_f32 v[90:91], v[86:87], v[156:157], v[164:165] op_sel_hi:[1,0,1]
	v_pk_fma_f32 v[86:87], v[82:83], v[156:157], v[166:167] op_sel_hi:[1,0,1]
	v_mul_f32_e32 v82, v137, v137
	v_mul_f32_e32 v83, v97, v97
	v_mul_f32_e32 v145, v95, v95
	v_mul_f32_e32 v147, v93, v93
	v_pk_fma_f32 v[84:85], v[84:85], v[156:157], v[148:149] op_sel_hi:[1,0,1]
	v_mul_f32_e32 v148, v91, v91
	v_mul_f32_e32 v149, v89, v89
	v_fmac_f32_e32 v82, v136, v136
	v_fmac_f32_e32 v83, v96, v96
	v_fmac_f32_e32 v145, v94, v94
	v_fmac_f32_e32 v147, v92, v92
	v_mul_f32_e32 v150, v87, v87
	v_mul_f32_e32 v151, v85, v85
	v_fmac_f32_e32 v148, v90, v90
	v_fmac_f32_e32 v149, v88, v88
	v_add_f32_e32 v82, v82, v83
	v_add_f32_e32 v83, v145, v147
	v_fmac_f32_e32 v150, v86, v86
	v_fmac_f32_e32 v151, v84, v84
	v_add_f32_e32 v145, v148, v149
	v_add_f32_e32 v82, v82, v83
	v_add_f32_e32 v82, v82, v145
	v_add_f32_e32 v83, v150, v151
	v_add_f32_e32 v82, v82, v83
	ds_bpermute_b32 v83, v161, v82
	s_waitcnt lgkmcnt(0)
	v_add_f32_e32 v82, v82, v83
	ds_bpermute_b32 v83, v163, v82
	s_and_saveexec_b64 s[2:3], vcc
	s_cbranch_execz .LBB0_1040
	v_lshl_add_u32 v143, v143, 4, s1
	s_waitcnt lgkmcnt(0)
	v_add_f32_e32 v82, v82, v83
	ds_write_b32 v143, v82
; __device__ __forceinline__ f32x4 bf4_to_f32(u32x2 w) { f32x4 r; r[0] = __uint_as_float(w.x << 16); r[1] = __uint_as_float(w.x & 0xffff0000u); r[2] = __uint_as_float(w.y << 16); r[3] = __uint_as_float(w.y & 0xffff0000u); return r; }
;     __device__ __forceinline__ void fused(f32x4 (&acc)[2][2][4][2], const Unit& u, int wr, int wc, int fr, int fq, PG8_LAS unsigned char* lds, int wid, int lane) const {
;     ...
;             for (int m = 0; m < 4; ++m) { const int r = ai * HALF + wr * 64 + m * 16 + fr; const size_t off = (size_t)(u.pm * BM + r) * 2048 + col0; float s = 0.f;
;                 const float rr = __builtin_amdgcn_rcpf(r2[ai * 4 + m] * (1.0f / 2048.0f) + 1e-5f);
; #pragma unroll
;                 for (int bj = 0; bj < 2; ++bj)
; #pragma unroll
;                     for (int n = 0; n < 2; ++n) { const f32x4 bs = bf4_to_f32(*(const u32x2*)(base + off + bj * HALF + n * 16)); const f32x4 o = bs + acc[ai][bj][m][n] * rr; acc[ai][bj][m][n] = o;
;                         s += (o[0] * o[0] + o[1] * o[1]) + (o[2] * o[2] + o[3] * o[3]); }
;                 s += __shfl_xor(s, 16); s += __shfl_xor(s, 32);
;                 if (fq == 0) P[r * 4 + wc] = s; }
.LBB0_1040:
	s_or_b64 exec, exec, s[2:3]
	v_or_b32_e32 v143, 48, v162
	v_add_u32_e32 v82, s0, v143
	s_waitcnt lgkmcnt(0)
	v_ashrrev_i32_e32 v83, 31, v82
	v_lshlrev_b64 v[148:149], 12, v[82:83]
	v_lshl_add_u64 v[148:149], s[70:71], 0, v[148:149]
	v_lshl_add_u64 v[148:149], v[148:149], 0, v[140:141]
	s_waitcnt vmcnt(0)
	v_mov_b64_e32 v[150:151], v[218:219]
	v_mov_b64_e32 v[152:153], v[220:221]
	v_mov_b64_e32 v[154:155], v[222:223]
	v_mov_b64_e32 v[148:149], v[224:225]
	s_nop 0
	v_fmac_f32_e32 v138, 0x3a000000, v139
	v_rcp_f32_e32 v138, v138
	s_waitcnt vmcnt(3)
	v_lshlrev_b32_e32 v156, 16, v150
	v_and_b32_e32 v157, 0xffff0000, v150
	v_lshlrev_b32_e32 v150, 16, v151
	v_and_b32_e32 v151, 0xffff0000, v151
	s_waitcnt vmcnt(2)
	v_lshlrev_b32_e32 v158, 16, v152
	v_and_b32_e32 v159, 0xffff0000, v152
	v_lshlrev_b32_e32 v152, 16, v153
	v_and_b32_e32 v153, 0xffff0000, v153
	s_waitcnt vmcnt(1)
	v_lshlrev_b32_e32 v164, 16, v154
	v_and_b32_e32 v165, 0xffff0000, v154
	v_lshlrev_b32_e32 v154, 16, v155
	v_and_b32_e32 v155, 0xffff0000, v155
	s_waitcnt vmcnt(0)
	v_lshlrev_b32_e32 v166, 16, v148
	v_and_b32_e32 v167, 0xffff0000, v148
	v_lshlrev_b32_e32 v148, 16, v149
	v_and_b32_e32 v149, 0xffff0000, v149
	v_pk_fma_f32 v[80:81], v[80:81], v[138:139], v[150:151] op_sel_hi:[1,0,1]
	v_pk_fma_f32 v[78:79], v[78:79], v[138:139], v[156:157] op_sel_hi:[1,0,1]
	v_pk_fma_f32 v[76:77], v[76:77], v[138:139], v[152:153] op_sel_hi:[1,0,1]
	v_pk_fma_f32 v[74:75], v[74:75], v[138:139], v[158:159] op_sel_hi:[1,0,1]
	v_pk_fma_f32 v[72:73], v[72:73], v[138:139], v[154:155] op_sel_hi:[1,0,1]
	v_pk_fma_f32 v[70:71], v[70:71], v[138:139], v[164:165] op_sel_hi:[1,0,1]
	v_pk_fma_f32 v[68:69], v[68:69], v[138:139], v[148:149] op_sel_hi:[1,0,1]
	v_pk_fma_f32 v[66:67], v[66:67], v[138:139], v[166:167] op_sel_hi:[1,0,1]
	v_mul_f32_e32 v138, v79, v79
	v_mul_f32_e32 v139, v81, v81
	v_mul_f32_e32 v141, v75, v75
	v_mul_f32_e32 v145, v77, v77
	v_mul_f32_e32 v147, v71, v71
	v_mul_f32_e32 v148, v73, v73
	v_fmac_f32_e32 v138, v78, v78
	v_fmac_f32_e32 v139, v80, v80
	v_fmac_f32_e32 v141, v74, v74
	v_fmac_f32_e32 v145, v76, v76
	v_mul_f32_e32 v149, v67, v67
	v_mul_f32_e32 v150, v69, v69
	v_fmac_f32_e32 v147, v70, v70
	v_fmac_f32_e32 v148, v72, v72
	v_add_f32_e32 v138, v138, v139
	v_add_f32_e32 v139, v141, v145
	v_fmac_f32_e32 v149, v66, v66
	v_fmac_f32_e32 v150, v68, v68
	v_add_f32_e32 v141, v147, v148
	v_add_f32_e32 v138, v138, v139
	v_add_f32_e32 v138, v138, v141
	v_add_f32_e32 v139, v149, v150
	v_add_f32_e32 v138, v138, v139
	ds_bpermute_b32 v139, v161, v138
	s_waitcnt lgkmcnt(0)
	v_add_f32_e32 v138, v138, v139
	ds_bpermute_b32 v139, v163, v138
	s_and_saveexec_b64 s[2:3], vcc
	s_cbranch_execz .LBB0_1042
	v_lshl_add_u32 v141, v143, 4, s1
	s_waitcnt lgkmcnt(0)
	v_add_f32_e32 v138, v138, v139
	ds_write_b32 v141, v138
.LBB0_1042:
	s_or_b64 exec, exec, s[2:3]
	v_add_u32_e32 v143, 0x80, v162
	v_add_u32_e32 v138, s0, v143
	s_waitcnt lgkmcnt(0)
	v_ashrrev_i32_e32 v139, 31, v138
	v_lshlrev_b64 v[148:149], 12, v[138:139]
	v_lshl_add_u64 v[148:149], s[70:71], 0, v[148:149]
	v_mov_b32_e32 v141, 0
	v_lshl_add_u64 v[148:149], v[148:149], 0, v[140:141]
	s_waitcnt vmcnt(0)
	v_mov_b64_e32 v[150:151], v[226:227]
	v_mov_b64_e32 v[152:153], v[228:229]
	v_mov_b64_e32 v[154:155], v[230:231]
	v_mov_b64_e32 v[148:149], v[232:233]
	s_nop 0
	v_mov_b32_e32 v145, 0x3727c5ac
	v_fmamk_f32 v142, v142, 0x3a000000, v145
	v_rcp_f32_e32 v142, v142
	s_waitcnt vmcnt(3)
	v_lshlrev_b32_e32 v156, 16, v150
	v_and_b32_e32 v157, 0xffff0000, v150
	v_lshlrev_b32_e32 v150, 16, v151
	v_and_b32_e32 v151, 0xffff0000, v151
	s_waitcnt vmcnt(2)
	v_lshlrev_b32_e32 v158, 16, v152
	v_and_b32_e32 v159, 0xffff0000, v152
	v_lshlrev_b32_e32 v152, 16, v153
	v_and_b32_e32 v153, 0xffff0000, v153
	s_waitcnt vmcnt(1)
	v_lshlrev_b32_e32 v164, 16, v154
	v_and_b32_e32 v165, 0xffff0000, v154
	v_lshlrev_b32_e32 v154, 16, v155
	v_and_b32_e32 v155, 0xffff0000, v155
	s_waitcnt vmcnt(0)
	v_lshlrev_b32_e32 v166, 16, v148
	v_and_b32_e32 v167, 0xffff0000, v148
	v_lshlrev_b32_e32 v148, 16, v149
	v_and_b32_e32 v149, 0xffff0000, v149
	v_pk_fma_f32 v[64:65], v[64:65], v[142:143], v[150:151] op_sel_hi:[1,0,1]
	v_pk_fma_f32 v[62:63], v[62:63], v[142:143], v[156:157] op_sel_hi:[1,0,1]
	v_pk_fma_f32 v[60:61], v[60:61], v[142:143], v[152:153] op_sel_hi:[1,0,1]
	v_pk_fma_f32 v[58:59], v[58:59], v[142:143], v[158:159] op_sel_hi:[1,0,1]
	v_pk_fma_f32 v[56:57], v[56:57], v[142:143], v[154:155] op_sel_hi:[1,0,1]
	v_pk_fma_f32 v[54:55], v[54:55], v[142:143], v[164:165] op_sel_hi:[1,0,1]
	v_pk_fma_f32 v[52:53], v[52:53], v[142:143], v[148:149] op_sel_hi:[1,0,1]
	v_pk_fma_f32 v[50:51], v[50:51], v[142:143], v[166:167] op_sel_hi:[1,0,1]
	v_mul_f32_e32 v142, v63, v63
	v_mul_f32_e32 v147, v65, v65
	v_mul_f32_e32 v148, v59, v59
	v_mul_f32_e32 v149, v61, v61
	v_mul_f32_e32 v150, v55, v55
	v_mul_f32_e32 v151, v57, v57
	v_fmac_f32_e32 v142, v62, v62
	v_fmac_f32_e32 v147, v64, v64
	v_fmac_f32_e32 v148, v58, v58
	v_fmac_f32_e32 v149, v60, v60
	v_mul_f32_e32 v152, v51, v51
	v_mul_f32_e32 v153, v53, v53
	v_fmac_f32_e32 v150, v54, v54
	v_fmac_f32_e32 v151, v56, v56
	v_add_f32_e32 v142, v142, v147
	v_add_f32_e32 v147, v148, v149
	v_fmac_f32_e32 v152, v50, v50
	v_fmac_f32_e32 v153, v52, v52
	v_add_f32_e32 v148, v150, v151
	v_add_f32_e32 v142, v142, v147
	v_add_f32_e32 v142, v142, v148
	v_add_f32_e32 v147, v152, v153
	v_add_f32_e32 v142, v142, v147
	ds_bpermute_b32 v147, v161, v142
	s_waitcnt lgkmcnt(0)
	v_add_f32_e32 v142, v142, v147
	ds_bpermute_b32 v147, v163, v142
	s_and_saveexec_b64 s[2:3], vcc
	s_cbranch_execz .LBB0_1044
	v_lshl_add_u32 v143, v143, 4, s1
	s_waitcnt lgkmcnt(0)
	v_add_f32_e32 v142, v142, v147
	ds_write_b32 v143, v142
; __device__ __forceinline__ f32x4 bf4_to_f32(u32x2 w) { f32x4 r; r[0] = __uint_as_float(w.x << 16); r[1] = __uint_as_float(w.x & 0xffff0000u); r[2] = __uint_as_float(w.y << 16); r[3] = __uint_as_float(w.y & 0xffff0000u); return r; }
;     __device__ __forceinline__ void fused(f32x4 (&acc)[2][2][4][2], const Unit& u, int wr, int wc, int fr, int fq, PG8_LAS unsigned char* lds, int wid, int lane) const {
;     ...
;             for (int m = 0; m < 4; ++m) { const int r = ai * HALF + wr * 64 + m * 16 + fr; const size_t off = (size_t)(u.pm * BM + r) * 2048 + col0; float s = 0.f;
;                 const float rr = __builtin_amdgcn_rcpf(r2[ai * 4 + m] * (1.0f / 2048.0f) + 1e-5f);
; #pragma unroll
;                 for (int bj = 0; bj < 2; ++bj)
; #pragma unroll
;                     for (int n = 0; n < 2; ++n) { const f32x4 bs = bf4_to_f32(*(const u32x2*)(base + off + bj * HALF + n * 16)); const f32x4 o = bs + acc[ai][bj][m][n] * rr; acc[ai][bj][m][n] = o;
;                         s += (o[0] * o[0] + o[1] * o[1]) + (o[2] * o[2] + o[3] * o[3]); }
;                 s += __shfl_xor(s, 16); s += __shfl_xor(s, 32);
;                 if (fq == 0) P[r * 4 + wc] = s; }
.LBB0_1044:
	s_or_b64 exec, exec, s[2:3]
	s_waitcnt lgkmcnt(0)
	v_add_u32_e32 v147, 0x90, v162
	v_add_u32_e32 v142, s0, v147
	v_ashrrev_i32_e32 v143, 31, v142
	v_lshlrev_b64 v[148:149], 12, v[142:143]
	v_lshl_add_u64 v[148:149], s[70:71], 0, v[148:149]
	v_lshl_add_u64 v[148:149], v[148:149], 0, v[140:141]
	s_waitcnt vmcnt(0)
	v_mov_b64_e32 v[150:151], v[234:235]
	v_mov_b64_e32 v[152:153], v[236:237]
	v_mov_b64_e32 v[154:155], v[238:239]
	v_mov_b64_e32 v[148:149], v[240:241]
	s_nop 0
	v_fmac_f32_e32 v145, 0x3a000000, v144
	v_rcp_f32_e32 v144, v145
	s_waitcnt vmcnt(3)
	v_lshlrev_b32_e32 v156, 16, v150
	v_and_b32_e32 v157, 0xffff0000, v150
	v_lshlrev_b32_e32 v150, 16, v151
	v_and_b32_e32 v151, 0xffff0000, v151
	s_waitcnt vmcnt(2)
	v_lshlrev_b32_e32 v158, 16, v152
	v_and_b32_e32 v159, 0xffff0000, v152
	v_lshlrev_b32_e32 v152, 16, v153
	v_and_b32_e32 v153, 0xffff0000, v153
	s_waitcnt vmcnt(1)
	v_lshlrev_b32_e32 v164, 16, v154
	v_and_b32_e32 v165, 0xffff0000, v154
	v_lshlrev_b32_e32 v154, 16, v155
	v_and_b32_e32 v155, 0xffff0000, v155
	s_waitcnt vmcnt(0)
	v_lshlrev_b32_e32 v166, 16, v148
	v_and_b32_e32 v167, 0xffff0000, v148
	v_lshlrev_b32_e32 v148, 16, v149
	v_and_b32_e32 v149, 0xffff0000, v149
	v_pk_fma_f32 v[48:49], v[48:49], v[144:145], v[150:151] op_sel_hi:[1,0,1]
	v_pk_fma_f32 v[46:47], v[46:47], v[144:145], v[156:157] op_sel_hi:[1,0,1]
	v_pk_fma_f32 v[44:45], v[44:45], v[144:145], v[152:153] op_sel_hi:[1,0,1]
	v_pk_fma_f32 v[42:43], v[42:43], v[144:145], v[158:159] op_sel_hi:[1,0,1]
	v_pk_fma_f32 v[40:41], v[40:41], v[144:145], v[154:155] op_sel_hi:[1,0,1]
	v_pk_fma_f32 v[38:39], v[38:39], v[144:145], v[164:165] op_sel_hi:[1,0,1]
	v_pk_fma_f32 v[36:37], v[36:37], v[144:145], v[148:149] op_sel_hi:[1,0,1]
	v_pk_fma_f32 v[34:35], v[34:35], v[144:145], v[166:167] op_sel_hi:[1,0,1]
	v_mul_f32_e32 v141, v47, v47
	v_mul_f32_e32 v144, v49, v49
	v_mul_f32_e32 v145, v43, v43
	v_mul_f32_e32 v148, v45, v45
	v_mul_f32_e32 v149, v39, v39
	v_mul_f32_e32 v150, v41, v41
	v_fmac_f32_e32 v141, v46, v46
	v_fmac_f32_e32 v144, v48, v48
	v_fmac_f32_e32 v145, v42, v42
	v_fmac_f32_e32 v148, v44, v44
	v_mul_f32_e32 v151, v35, v35
	v_mul_f32_e32 v152, v37, v37
	v_fmac_f32_e32 v149, v38, v38
	v_fmac_f32_e32 v150, v40, v40
	v_add_f32_e32 v141, v141, v144
	v_add_f32_e32 v144, v145, v148
	v_fmac_f32_e32 v151, v34, v34
	v_fmac_f32_e32 v152, v36, v36
	v_add_f32_e32 v145, v149, v150
	v_add_f32_e32 v141, v141, v144
	v_add_f32_e32 v141, v141, v145
	v_add_f32_e32 v144, v151, v152
	v_add_f32_e32 v141, v141, v144
	ds_bpermute_b32 v144, v161, v141
	s_waitcnt lgkmcnt(0)
	v_add_f32_e32 v141, v141, v144
	ds_bpermute_b32 v144, v163, v141
	s_and_saveexec_b64 s[2:3], vcc
	s_cbranch_execz .LBB0_1046
	v_lshl_add_u32 v145, v147, 4, s1
	s_waitcnt lgkmcnt(0)
	v_add_f32_e32 v141, v141, v144
	ds_write_b32 v145, v141
; __device__ __forceinline__ f32x4 bf4_to_f32(u32x2 w) { f32x4 r; r[0] = __uint_as_float(w.x << 16); r[1] = __uint_as_float(w.x & 0xffff0000u); r[2] = __uint_as_float(w.y << 16); r[3] = __uint_as_float(w.y & 0xffff0000u); return r; }
;     __device__ __forceinline__ void fused(f32x4 (&acc)[2][2][4][2], const Unit& u, int wr, int wc, int fr, int fq, PG8_LAS unsigned char* lds, int wid, int lane) const {
;     ...
;             for (int m = 0; m < 4; ++m) { const int r = ai * HALF + wr * 64 + m * 16 + fr; const size_t off = (size_t)(u.pm * BM + r) * 2048 + col0; float s = 0.f;
;                 const float rr = __builtin_amdgcn_rcpf(r2[ai * 4 + m] * (1.0f / 2048.0f) + 1e-5f);
; #pragma unroll
;                 for (int bj = 0; bj < 2; ++bj)
; #pragma unroll
;                     for (int n = 0; n < 2; ++n) { const f32x4 bs = bf4_to_f32(*(const u32x2*)(base + off + bj * HALF + n * 16)); const f32x4 o = bs + acc[ai][bj][m][n] * rr; acc[ai][bj][m][n] = o;
;                         s += (o[0] * o[0] + o[1] * o[1]) + (o[2] * o[2] + o[3] * o[3]); }
;                 s += __shfl_xor(s, 16); s += __shfl_xor(s, 32);
;                 if (fq == 0) P[r * 4 + wc] = s; }
.LBB0_1046:
	s_or_b64 exec, exec, s[2:3]
	v_add_u32_e32 v147, 0xa0, v162
	s_waitcnt lgkmcnt(0)
	v_add_u32_e32 v144, s0, v147
	v_ashrrev_i32_e32 v145, 31, v144
	v_lshlrev_b64 v[148:149], 12, v[144:145]
	v_lshl_add_u64 v[148:149], s[70:71], 0, v[148:149]
	v_mov_b32_e32 v141, 0
	v_lshl_add_u64 v[148:149], v[148:149], 0, v[140:141]
	s_waitcnt vmcnt(0)
	v_mov_b64_e32 v[150:151], v[244:245]
	v_mov_b64_e32 v[152:153], v[246:247]
	v_mov_b64_e32 v[154:155], v[248:249]
	v_mov_b64_e32 v[156:157], v[250:251]
	v_mov_b32_e32 v148, 0x3727c5ac
	v_fmamk_f32 v146, v146, 0x3a000000, v148
	v_rcp_f32_e32 v146, v146
	s_waitcnt vmcnt(3)
	v_lshlrev_b32_e32 v158, 16, v150
	v_and_b32_e32 v159, 0xffff0000, v150
	v_lshlrev_b32_e32 v150, 16, v151
	v_and_b32_e32 v151, 0xffff0000, v151
	s_waitcnt vmcnt(2)
	v_lshlrev_b32_e32 v164, 16, v152
	v_and_b32_e32 v165, 0xffff0000, v152
	v_lshlrev_b32_e32 v152, 16, v153
	v_and_b32_e32 v153, 0xffff0000, v153
	s_waitcnt vmcnt(1)
	v_lshlrev_b32_e32 v166, 16, v154
	v_and_b32_e32 v167, 0xffff0000, v154
	v_lshlrev_b32_e32 v154, 16, v155
	v_and_b32_e32 v155, 0xffff0000, v155
	s_waitcnt vmcnt(0)
	v_lshlrev_b32_e32 v168, 16, v156
	v_and_b32_e32 v169, 0xffff0000, v156
	v_lshlrev_b32_e32 v156, 16, v157
	v_and_b32_e32 v157, 0xffff0000, v157
	v_pk_fma_f32 v[32:33], v[32:33], v[146:147], v[150:151] op_sel_hi:[1,0,1]
	v_pk_fma_f32 v[30:31], v[30:31], v[146:147], v[158:159] op_sel_hi:[1,0,1]
	v_pk_fma_f32 v[28:29], v[28:29], v[146:147], v[152:153] op_sel_hi:[1,0,1]
	v_pk_fma_f32 v[26:27], v[26:27], v[146:147], v[164:165] op_sel_hi:[1,0,1]
	v_pk_fma_f32 v[24:25], v[24:25], v[146:147], v[154:155] op_sel_hi:[1,0,1]
	v_pk_fma_f32 v[22:23], v[22:23], v[146:147], v[166:167] op_sel_hi:[1,0,1]
	v_pk_fma_f32 v[20:21], v[20:21], v[146:147], v[156:157] op_sel_hi:[1,0,1]
	v_pk_fma_f32 v[18:19], v[18:19], v[146:147], v[168:169] op_sel_hi:[1,0,1]
	v_mul_f32_e32 v146, v31, v31
	v_mul_f32_e32 v149, v33, v33
	v_mul_f32_e32 v150, v27, v27
	v_mul_f32_e32 v151, v29, v29
	v_mul_f32_e32 v152, v23, v23
	v_mul_f32_e32 v153, v25, v25
	v_fmac_f32_e32 v146, v30, v30
	v_fmac_f32_e32 v149, v32, v32
	v_fmac_f32_e32 v150, v26, v26
	v_fmac_f32_e32 v151, v28, v28
	v_mul_f32_e32 v154, v19, v19
	v_mul_f32_e32 v155, v21, v21
	v_fmac_f32_e32 v152, v22, v22
	v_fmac_f32_e32 v153, v24, v24
	v_add_f32_e32 v146, v146, v149
	v_add_f32_e32 v149, v150, v151
	v_fmac_f32_e32 v154, v18, v18
	v_fmac_f32_e32 v155, v20, v20
	v_add_f32_e32 v150, v152, v153
	v_add_f32_e32 v146, v146, v149
	v_add_f32_e32 v146, v146, v150
	v_add_f32_e32 v149, v154, v155
	v_add_f32_e32 v146, v146, v149
	ds_bpermute_b32 v149, v161, v146
	s_waitcnt lgkmcnt(0)
	v_add_f32_e32 v146, v146, v149
	ds_bpermute_b32 v149, v163, v146
	s_and_saveexec_b64 s[2:3], vcc
	s_cbranch_execz .LBB0_1048
	v_lshl_add_u32 v147, v147, 4, s1
	s_waitcnt lgkmcnt(0)
	v_add_f32_e32 v146, v146, v149
	ds_write_b32 v147, v146
.LBB0_1048:
	s_or_b64 exec, exec, s[2:3]
	v_add_u32_e32 v164, 0xb0, v162
	v_add_u32_e32 v146, s0, v164
	v_ashrrev_i32_e32 v147, 31, v146
	v_lshlrev_b64 v[150:151], 12, v[146:147]
	v_lshl_add_u64 v[150:151], s[70:71], 0, v[150:151]
	v_lshl_add_u64 v[140:141], v[150:151], 0, v[140:141]
	s_waitcnt vmcnt(0)
	v_mov_b64_e32 v[150:151], v[252:253]
	v_mov_b64_e32 v[152:153], v[254:255]
	v_mov_b64_e32 v[154:155], v[188:189]
	v_mov_b64_e32 v[140:141], v[190:191]
	s_nop 0
	v_fmac_f32_e32 v148, 0x3a000000, v1
	v_rcp_f32_e32 v148, v148
	s_waitcnt vmcnt(3)
	v_lshlrev_b32_e32 v158, 16, v150
	v_and_b32_e32 v159, 0xffff0000, v150
	v_lshlrev_b32_e32 v150, 16, v151
	v_and_b32_e32 v151, 0xffff0000, v151
	s_waitcnt vmcnt(2)
	v_lshlrev_b32_e32 v166, 16, v152
	v_and_b32_e32 v167, 0xffff0000, v152
	v_lshlrev_b32_e32 v152, 16, v153
	v_and_b32_e32 v153, 0xffff0000, v153
	s_waitcnt vmcnt(1)
	v_lshlrev_b32_e32 v168, 16, v154
	v_and_b32_e32 v169, 0xffff0000, v154
	v_lshlrev_b32_e32 v170, 16, v155
	v_and_b32_e32 v171, 0xffff0000, v155
	s_waitcnt vmcnt(0)
	v_lshlrev_b32_e32 v172, 16, v140
	v_and_b32_e32 v173, 0xffff0000, v140
	v_lshlrev_b32_e32 v174, 16, v141
	v_and_b32_e32 v175, 0xffff0000, v141
	s_waitcnt lgkmcnt(0)
	v_pk_fma_f32 v[156:157], v[16:17], v[148:149], v[150:151] op_sel_hi:[1,0,1]
	v_pk_fma_f32 v[158:159], v[14:15], v[148:149], v[158:159] op_sel_hi:[1,0,1]
	v_pk_fma_f32 v[152:153], v[12:13], v[148:149], v[152:153] op_sel_hi:[1,0,1]
	v_pk_fma_f32 v[154:155], v[10:11], v[148:149], v[166:167] op_sel_hi:[1,0,1]
	v_pk_fma_f32 v[140:141], v[8:9], v[148:149], v[170:171] op_sel_hi:[1,0,1]
	v_pk_fma_f32 v[150:151], v[6:7], v[148:149], v[168:169] op_sel_hi:[1,0,1]
	v_pk_fma_f32 v[16:17], v[4:5], v[148:149], v[174:175] op_sel_hi:[1,0,1]
	v_pk_fma_f32 v[148:149], v[2:3], v[148:149], v[172:173] op_sel_hi:[1,0,1]
	v_mul_f32_e32 v1, v159, v159
	v_mul_f32_e32 v2, v157, v157
	v_mul_f32_e32 v3, v155, v155
	v_mul_f32_e32 v4, v153, v153
	v_mul_f32_e32 v5, v151, v151
	v_mul_f32_e32 v6, v141, v141
	v_fmac_f32_e32 v1, v158, v158
	v_fmac_f32_e32 v2, v156, v156
	v_fmac_f32_e32 v3, v154, v154
	v_fmac_f32_e32 v4, v152, v152
	v_mul_f32_e32 v7, v149, v149
	v_mul_f32_e32 v8, v17, v17
	v_fmac_f32_e32 v5, v150, v150
	v_fmac_f32_e32 v6, v140, v140
	v_add_f32_e32 v1, v1, v2
	v_add_f32_e32 v2, v3, v4
	v_fmac_f32_e32 v7, v148, v148
	v_fmac_f32_e32 v8, v16, v16
	v_add_f32_e32 v3, v5, v6
	v_add_f32_e32 v1, v1, v2
	v_add_f32_e32 v1, v1, v3
	v_add_f32_e32 v2, v7, v8
	v_add_f32_e32 v1, v1, v2
	ds_bpermute_b32 v2, v161, v1
	s_waitcnt lgkmcnt(0)
	v_add_f32_e32 v1, v1, v2
	ds_bpermute_b32 v2, v163, v1
	s_and_saveexec_b64 s[2:3], vcc
	s_cbranch_execz .LBB0_1050
	v_lshl_add_u32 v3, v164, 4, s1
	s_waitcnt lgkmcnt(0)
	v_add_f32_e32 v1, v1, v2
	ds_write_b32 v3, v1
